# baseline (speedup 1.0000x reference)
; __device__ __forceinline__ void nsa_quad(const Params& p, int qd, int g, float* slds, const int lane_in) {
;     ...
;   const int nv = my_t >= 31 ? ((my_t - 31) >> 4) + 1 : 0;
;   const int tmax = t0 + 3;
;   const int nvmax = tmax >= 31 ? ((tmax - 31) >> 4) + 1 : 0;
;   const int nch = (nvmax + 63) >> 6;
;   const bf16_t* kc = ((bf16_t*)(p.ws + OFF_kcmp)) + (long)g * 1024 * 64;
;   const bf16_t* vc = ((bf16_t*)(p.ws + OFF_vct)) + (long)g * 16 * 4096;
;   {
;     float m = NEGF, l = 0.f;
;     ...
;     const int nvmin = t0 >= 31 ? ((t0 - 31) >> 4) + 1 : 0;
;     if (nch > 0) load_k(A, kc, loff);
;     for (int c = 0; c < nch; c += 2) {
;       if (c + 1 < nch) load_k(B, kc + (c + 1) * 4096, loff);
;       if ((c + 1) * 64 <= nvmin) { CSTAT(A, c, 0) } else { CSTAT(A, c, 1) }
.LBB0_574:
	v_subrev_u32_e32 v0, 31, v4
	s_sub_i32 s0, s90, 31
	v_ashrrev_i32_e32 v0, 4, v0
	s_ashr_i32 s0, s0, 4
	v_add_u32_e32 v0, 1, v0
	v_cmp_lt_i32_e32 vcc, 30, v4
	s_add_i32 s0, s0, 1
	s_cmp_gt_i32 s39, 7
	v_cndmask_b32_e32 v176, 0, v0, vcc
	v_cndmask_b32_e64 v0, 0, 1, s[58:59]
	s_cselect_b32 s31, s0, 0
	v_cmp_ne_u32_e64 s[0:1], 1, v0
	s_andn2_b64 vcc, exec, s[58:59]
	v_add_u32_e32 v178, -16, v176
	v_subrev_u32_e32 v173, 17, v176
	v_subrev_u32_e32 v180, 18, v176
	v_subrev_u32_e32 v177, 19, v176
	v_subrev_u32_e32 v182, 32, v176
	v_subrev_u32_e32 v179, 33, v176
	v_subrev_u32_e32 v184, 34, v176
	v_subrev_u32_e32 v181, 35, v176
	v_subrev_u32_e32 v186, 48, v176
	v_subrev_u32_e32 v183, 49, v176
	v_subrev_u32_e32 v188, 50, v176
	v_subrev_u32_e32 v185, 51, v176
	v_lshlrev_b32_e32 v194, 2, v3
	s_cbranch_vccnz .LBB0_646
	s_mov_b32 s36, 2
	v_mov_b32_e32 v48, 0
	v_mov_b32_e32 v195, 0xf149f2ca
	s_movk_i32 s37, 0x80
	s_movk_i32 s62, 0x2000
	.p2align 6

; __device__ __forceinline__ void nsa_quad(const Params& p, int qd, int g, float* slds, const int lane_in) {
;     ...
;     const float invl = 1.f / fmaxf(l, 1e-30f);
;     f32x4 oacc[4];
; #pragma unroll
;     for (int dt = 0; dt < 4; ++dt) oacc[dt] = f32x4{0.f, 0.f, 0.f, 0.f};
;     float* sl = slds + qi * 512;
;     ...
;     if (nch > 0) { load_k(A, kc, loff); load_v(A, vc, loff); }
;     for (int c = 0; c < nch; c += 2) {
;       if (c + 1 < nch) { load_k(B, kc + (c + 1) * 4096, loff); load_v(B, vc + (c + 1) * 4096, loff); }
;       if ((c + 1) * 64 <= nvmin) { CP2(A, c, 0) } else { CP2(A, c, 1) }
.LBB0_594:
	s_and_b64 vcc, exec, s[0:1]
	s_movk_i32 s12, 0x1000
	s_cbranch_vccnz .LBB0_647
	v_div_scale_f32 v0, s[0:1], v3, v3, 1.0
	s_waitcnt lgkmcnt(1)
	v_rcp_f32_e32 v36, v0
	v_div_scale_f32 v37, vcc, 1.0, v3, 1.0
	v_readlane_b32 s2, v255, 50
	v_fma_f32 v38, -v0, v36, 1.0
	v_fmac_f32_e32 v36, v38, v36
	v_mul_f32_e32 v38, v37, v36
	v_fma_f32 v39, -v0, v38, v37
	v_fmac_f32_e32 v38, v39, v36
	v_fma_f32 v0, -v0, v38, v37
	v_div_fmas_f32 v0, v0, v36, v38
	v_div_fixup_f32 v190, v0, v3, 1.0
	v_lshlrev_b32_e32 v0, 11, v2
	v_mov_b32_e32 v2, v1
	v_mov_b32_e32 v3, v1
	v_add3_u32 v196, v0, v194, s2
	v_mov_b32_e32 v0, v1
	v_mov_b64_e32 v[134:135], v[2:3]
	v_mov_b64_e32 v[138:139], v[2:3]
	v_mov_b64_e32 v[142:143], v[2:3]
	v_mov_b64_e32 v[146:147], v[2:3]
	s_mov_b32 s9, 0
	v_cmp_eq_u32_e64 s[0:1], 0, v192
	s_mov_b32 s8, 2
	v_mov_b32_e32 v187, v176
	v_mov_b32_e32 v191, v190
	s_movk_i32 s2, 0x2000
	v_mov_b64_e32 v[132:133], v[0:1]
	v_mov_b64_e32 v[136:137], v[0:1]
	v_mov_b64_e32 v[140:141], v[0:1]
	v_mov_b64_e32 v[144:145], v[0:1]
	.p2align 6

; __device__ __forceinline__ void nsa_quad(const Params& p, int qd, int g, float* slds, const int lane_in) {
;     ...
;   for (int qs = 0; qs < 4; ++qs) {
;     const int jmax = nch * 16;
;     const float* sl = slds + qs * 512;
;     unsigned key0, key1, key2, key3;
;     {
;       unsigned kk[4];
; #pragma unroll
;       for (int i = 0; i < 4; ++i) {
;         const int j = lane * 4 + i;
;         float imp = 0.f;
;         if (j < jmax) imp += sl[j];
;         if (j >= 1 && j - 1 < jmax) imp += sl[256 + j - 1];
;         const bool candidate = (j >= 1) && (j <= cur - 2);
;         kk[i] = candidate ? (__float_as_uint(imp) + 1u) : 0u;
;       }
;       key0 = kk[0]; key1 = kk[1]; key2 = kk[2]; key3 = kk[3];
;     }
;     __builtin_amdgcn_fence(__ATOMIC_RELEASE, "wavefront");
;     __builtin_amdgcn_wave_barrier();
;     bool s0, s1, s2, s3;
;     if (ncand <= ktarget) {
.LBB0_649:
	s_add_i32 s59, s59, 1
	s_cmp_eq_u32 s59, 4
	s_cbranch_scc1 .LBB0_701
	.p2align 6

; __device__ __forceinline__ float bflo(unsigned w) { return __uint_as_float(w << 16); }
; __device__ __forceinline__ float bfhi(unsigned w) { return __uint_as_float(w & 0xffff0000u); }
; #define PSEL(QA, R) (__builtin_amdgcn_readfirstlane(sel[(QA) * 512 + (R)]))
; #define PLOAD8(QA, BASE, BLK) { unsigned off_ = loff; asm volatile("" : "+v"(off_)); const char* cb_ = (BASE) + (long)(BLK) * 4096; \
;       _Pragma("unroll") for (int i_ = 0; i_ < 4; ++i_) kvb[QA][i_] = *(const l64x2*)(cb_ + i_ * 1024 + off_); }
; __device__ __forceinline__ void nsa_quad(const Params& p, int qd, int g, float* slds, const int lane_in) {
;     ...
;     if (npriv > 0) {
;       typedef long l64x2 __attribute__((ext_vector_type(2)));
;       l64x2 kvb[4][4];
;       const char* ks8 = (const char*)(p.ws + OFF_ks8) + (long)g * 256 * 4096;
;       const char* vs8 = (const char*)(p.ws + OFF_vs8) + (long)g * 256 * 4096;
;       long q8_0, q8_1;
;       {
;         const u32x4 qa_ = __builtin_bit_cast(u32x4, qst[0]), qb_ = __builtin_bit_cast(u32x4, qst[64]);
;         const unsigned a0 = pack_fp8x4(bflo(qa_[0]), bfhi(qa_[0]), bflo(qa_[1]), bfhi(qa_[1]));
;         const unsigned a1 = pack_fp8x4(bflo(qa_[2]), bfhi(qa_[2]), bflo(qa_[3]), bfhi(qa_[3]));
;         const unsigned b0 = pack_fp8x4(bflo(qb_[0]), bfhi(qb_[0]), bflo(qb_[1]), bfhi(qb_[1]));
;         const unsigned b1 = pack_fp8x4(bflo(qb_[2]), bfhi(qb_[2]), bflo(qb_[3]), bfhi(qb_[3]));
;         q8_0 = (long)(((unsigned long long)a1 << 32) | (unsigned long long)a0);
;         q8_1 = (long)(((unsigned long long)b1 << 32) | (unsigned long long)b0);
;       }
;     ...
; #pragma unroll
;       for (int qa = 0; qa < 4; ++qa) { const int blk = PSEL(qa, 0); PLOAD8(qa, ks8, blk) }
; #pragma unroll
;       for (int dt = 0; dt < 4; ++dt) oacc[dt] *= 256.f;
;       for (int r = 0; r < npriv; ++r) {
;         f32x4 sc[4];
; #pragma unroll
;         for (int tile = 0; tile < 4; ++tile) sc[tile] = f32x4{0.f, 0.f, 0.f, 0.f};
; #pragma unroll
;         for (int qa = 0; qa < 4; ++qa) {
;           const bool mine = (qi == qa);
;           const long qm0 = mine ? q8_0 : 0L, qm1 = mine ? q8_1 : 0L;
.LBB0_711:
	v_readlane_b32 s0, v255, 57
	v_readlane_b32 s1, v255, 58
	s_sub_i32 s0, s0, s1
	s_min_i32 s12, s0, s91
	s_cmp_lt_i32 s12, 1
	s_cbranch_scc1 .LBB0_726
	v_mov_b32_e32 v0, s76
	s_waitcnt vmcnt(0)
	ds_read_b32 v68, v0
	s_waitcnt lgkmcnt(2)
	ds_read_b128 v[148:151], v2 offset:12288
	s_waitcnt lgkmcnt(2)
	ds_read_b128 v[152:155], v2 offset:13312
	v_mov_b32_e32 v69, v164
	s_waitcnt lgkmcnt(2)
	v_readfirstlane_b32 s0, v68
	ds_read_b32 v84, v0 offset:2048
	s_ashr_i32 s1, s0, 31
	s_lshl_b64 s[0:1], s[0:1], 12
	s_add_u32 s0, s77, s0
	s_addc_u32 s1, s94, s1
	global_load_dwordx4 v[80:83], v69, s[0:1]
	global_load_dwordx4 v[76:79], v69, s[0:1] offset:1024
	global_load_dwordx4 v[72:75], v69, s[0:1] offset:2048
	s_nop 0
	global_load_dwordx4 v[68:71], v69, s[0:1] offset:3072
	s_waitcnt lgkmcnt(0)
	v_readfirstlane_b32 s0, v84
	v_mov_b32_e32 v84, v164
	ds_read_b32 v116, v0 offset:4096
	s_ashr_i32 s1, s0, 31
	s_lshl_b64 s[0:1], s[0:1], 12
	s_add_u32 s0, s77, s0
	s_addc_u32 s1, s94, s1
	global_load_dwordx4 v[96:99], v84, s[0:1]
	global_load_dwordx4 v[92:95], v84, s[0:1] offset:1024
	global_load_dwordx4 v[88:91], v84, s[0:1] offset:2048
	s_nop 0
	global_load_dwordx4 v[84:87], v84, s[0:1] offset:3072
	s_waitcnt lgkmcnt(0)
	v_readfirstlane_b32 s0, v116
	v_mov_b32_e32 v116, v164
	ds_read_b32 v0, v0 offset:6144
	s_ashr_i32 s1, s0, 31
	s_lshl_b64 s[0:1], s[0:1], 12
	s_add_u32 s0, s77, s0
	s_addc_u32 s1, s94, s1
	global_load_dwordx4 v[128:131], v116, s[0:1]
	global_load_dwordx4 v[124:127], v116, s[0:1] offset:1024
	global_load_dwordx4 v[120:123], v116, s[0:1] offset:2048
	s_nop 0
	global_load_dwordx4 v[116:119], v116, s[0:1] offset:3072
	s_waitcnt lgkmcnt(0)
	v_readfirstlane_b32 s0, v0
	s_ashr_i32 s1, s0, 31
	s_lshl_b64 s[0:1], s[0:1], 12
	v_mov_b32_e32 v0, v164
	s_add_u32 s0, s77, s0
	s_addc_u32 s1, s94, s1
	global_load_dwordx4 v[132:135], v0, s[0:1] offset:3072
	global_load_dwordx4 v[136:139], v0, s[0:1] offset:2048
	global_load_dwordx4 v[140:143], v0, s[0:1] offset:1024
	global_load_dwordx4 v[144:147], v0, s[0:1]
	v_lshlrev_b32_e32 v0, 16, v148
	v_and_b32_e32 v148, 0xffff0000, v148
	v_mov_b32_e32 v162, v1
	v_cvt_pk_fp8_f32 v162, v0, v148
	v_lshlrev_b32_e32 v0, 16, v150
	v_and_b32_e32 v148, 0xffff0000, v150
	v_mov_b32_e32 v161, v1
	v_cvt_pk_fp8_f32 v161, v0, v148
	v_lshlrev_b32_e32 v0, 16, v151
	v_and_b32_e32 v148, 0xffff0000, v151
	v_mov_b32_e32 v168, v1
	v_cvt_pk_fp8_f32 v161, v0, v148 op_sel:[0,0,1]
	v_lshlrev_b32_e32 v0, 16, v152
	v_and_b32_e32 v148, 0xffff0000, v152
	v_cvt_pk_fp8_f32 v168, v0, v148
	v_lshlrev_b32_e32 v0, 16, v154
	v_and_b32_e32 v148, 0xffff0000, v154
	v_mov_b32_e32 v163, v1
	v_cvt_pk_fp8_f32 v163, v0, v148
	v_lshlrev_b32_e32 v156, 16, v149
	v_and_b32_e32 v149, 0xffff0000, v149
	v_cvt_pk_fp8_f32 v162, v156, v149 op_sel:[0,0,1]
	v_lshlrev_b32_e32 v149, 16, v153
	v_and_b32_e32 v150, 0xffff0000, v153
	v_lshlrev_b32_e32 v0, 16, v155
	v_and_b32_e32 v148, 0xffff0000, v155
	v_cvt_pk_fp8_f32 v168, v149, v150 op_sel:[0,0,1]
	v_cvt_pk_fp8_f32 v163, v0, v148 op_sel:[0,0,1]
	s_mov_b32 s0, 0x43800000
	v_mul_f32_e32 v114, s0, v114
	v_mul_f32_e32 v115, s0, v115
	v_mul_f32_e32 v112, s0, v112
	v_mul_f32_e32 v113, s0, v113
	v_mul_f32_e32 v110, s0, v110
	v_mul_f32_e32 v111, s0, v111
	v_mul_f32_e32 v108, s0, v108
	v_mul_f32_e32 v109, s0, v109
	v_mul_f32_e32 v106, s0, v106
	v_mul_f32_e32 v107, s0, v107
	v_mul_f32_e32 v104, s0, v104
	v_mul_f32_e32 v105, s0, v105
	v_mul_f32_e32 v102, s0, v102
	v_mul_f32_e32 v103, s0, v103
	v_mul_f32_e32 v100, s0, v100
	v_mul_f32_e32 v101, s0, v101
	v_cmp_eq_u32_e64 s[0:1], 0, v160
	v_cmp_eq_u32_e64 s[2:3], 1, v160
	v_cmp_eq_u32_e64 s[4:5], 2, v160
	v_cmp_eq_u32_e64 s[6:7], 3, v160
	v_cndmask_b32_e64 v149, 0, v161, s[0:1]
	v_cndmask_b32_e64 v148, 0, v162, s[0:1]
	v_cndmask_b32_e64 v151, 0, v163, s[0:1]
	v_cndmask_b32_e64 v150, 0, v168, s[0:1]
	v_cndmask_b32_e64 v153, 0, v161, s[2:3]
	v_cndmask_b32_e64 v152, 0, v162, s[2:3]
	v_cndmask_b32_e64 v155, 0, v163, s[2:3]
	v_cndmask_b32_e64 v154, 0, v168, s[2:3]
	v_cndmask_b32_e64 v157, 0, v161, s[4:5]
	v_cndmask_b32_e64 v156, 0, v162, s[4:5]
	v_cndmask_b32_e64 v159, 0, v163, s[4:5]
	v_cndmask_b32_e64 v158, 0, v168, s[4:5]
	v_cndmask_b32_e64 v161, 0, v161, s[6:7]
	v_cndmask_b32_e64 v160, 0, v162, s[6:7]
	v_cndmask_b32_e64 v163, 0, v163, s[6:7]
	v_cndmask_b32_e64 v162, 0, v168, s[6:7]
	s_mov_b32 s13, 0
	s_mov_b32 s14, s76
	v_readlane_b32 s88, v253, 37
	v_readlane_b32 s89, v253, 38
	v_readlane_b32 s91, v255, 54
	.p2align 6

; #define GATE(I) sigmoid_f(bf2f(((bf16_t*)(p.ws + OFF_proj))[(long)my_t * LDP + COL_NG + g * 12 + head * 3 + (I)]))
; __device__ __forceinline__ void nsa_quad(const Params& p, int qd, int g, float* slds, const int lane_in) {
;     ...
;     {
;       const float scl = GATE(1) / fmaxf(l, 1e-30f) * (npriv > 0 ? (1.f / 256.f) : 1.f);
; #pragma unroll
;       for (int dt = 0; dt < 4; ++dt)
; #pragma unroll
;         for (int j = 0; j < 4; ++j) ost[(dt * 4 + j) * 64] += oacc[dt][j] * scl;
;     }
;   }
;   }
;   {
;     int lane_w = lane; asm volatile("" : "+v"(lane_w));
;     const int fr = lane_w & 15, fq = lane_w >> 4;
;     const int qi = fr >> 2, head = fr & 3;
;     const int my_t = t0 + qi;
;     float* ost = slds + 2048 + lane_w;
;     bf16x8* qst = (bf16x8*)(slds + 3072) + lane_w;
;     const unsigned loff = (unsigned)(lane_w * 16);
;     const bf16_t* kw = ((bf16_t*)(p.ws + OFF_kwb)) + (long)g * S_ * 64;
;     const bf16_t* vw = ((bf16_t*)(p.ws + OFF_vwt)) + (long)g * S_ * 64;
;     float m = NEGF, l = 0.f;
;     f32x4 oacc[4];
; #pragma unroll
;     for (int dt = 0; dt < 4; ++dt) oacc[dt] = f32x4{0.f, 0.f, 0.f, 0.f};
;     const int lo = my_t - 511;
;     const int lo0 = t0 - 511;
;     const int c0 = (lo0 > 0 ? lo0 : 0) >> 6;
;     const int c1 = (t0 + 3) >> 6;
;     load_k(A, kw + (long)c0 * 4096, loff); load_v(A, vw + (long)c0 * 4096, loff);
;     for (int c = c0; c <= c1; c += 2) {
;       if (c + 1 <= c1) { load_k(B, kw + (long)(c + 1) * 4096, loff); load_v(B, vw + (long)(c + 1) * 4096, loff); }
.LBB0_727:
	v_readlane_b32 s2, v255, 42
	v_and_b32_e32 v0, 3, v3
	v_readlane_b32 s3, v255, 43
	v_mul_u32_u24_e32 v0, 3, v0
	v_lshlrev_b32_e32 v0, 1, v0
	s_waitcnt vmcnt(0)
	v_mov_b64_e32 v[68:69], s[2:3]
	v_mad_i64_i32 v[68:69], s[2:3], v165, s48, v[68:69]
	v_lshl_add_u64 v[68:69], v[68:69], 0, v[0:1]
	global_load_ushort v0, v[68:69], off
	s_waitcnt vmcnt(0)
	v_lshlrev_b32_e32 v0, 16, v0
	v_mul_f32_e32 v0, 0xbfb8aa3b, v0
	v_exp_f32_e32 v0, v0
	s_nop 0
	v_add_f32_e32 v0, 1.0, v0
	v_div_scale_f32 v68, s[2:3], v0, v0, 1.0
	v_rcp_f32_e32 v69, v68
	s_nop 0
	v_fma_f32 v70, -v68, v69, 1.0
	v_fmac_f32_e32 v69, v70, v69
	v_div_scale_f32 v70, vcc, 1.0, v0, 1.0
	v_mul_f32_e32 v71, v70, v69
	v_fma_f32 v72, -v68, v71, v70
	v_fmac_f32_e32 v71, v72, v69
	v_fma_f32 v68, -v68, v71, v70
	v_div_fmas_f32 v68, v68, v69, v71
	v_div_fixup_f32 v0, v68, v0, 1.0
	v_max_f32_e32 v68, v167, v167
	v_max_f32_e32 v68, 0xda24260, v68
	v_div_scale_f32 v69, s[2:3], v68, v68, v0
	v_rcp_f32_e32 v70, v69
	v_readlane_b32 s2, v255, 44
	v_fma_f32 v71, -v69, v70, 1.0
	v_fmac_f32_e32 v70, v71, v70
	v_div_scale_f32 v71, vcc, v0, v68, v0
	v_mul_f32_e32 v72, v71, v70
	v_fma_f32 v73, -v69, v72, v71
	v_fmac_f32_e32 v72, v73, v70
	v_fma_f32 v69, -v69, v72, v71
	v_div_fmas_f32 v69, v69, v70, v72
	v_div_fixup_f32 v0, v69, v68, v0
	v_mul_f32_e32 v0, s0, v0
	v_mad_u64_u32 v[2:3], s[0:1], v3, -12, v[2:3]
	ds_read2st64_b32 v[68:69], v2 offset0:32 offset1:33
	s_max_i32 s0, s90, 0x1ff
	s_addk_i32 s0, 0xfe01
	s_lshr_b32 s80, s0, 6
	s_lshl_b64 s[0:1], s[80:81], 13
	s_waitcnt lgkmcnt(0)
	v_fma_f32 v3, v100, v0, v68
	v_fmac_f32_e32 v69, v101, v0
	ds_write2st64_b32 v2, v3, v69 offset0:32 offset1:33
	ds_read2st64_b32 v[68:69], v2 offset0:34 offset1:35
	s_add_u32 s0, s2, s0
	v_readlane_b32 s2, v255, 45
	s_addc_u32 s1, s2, s1
	s_cmp_le_i32 s80, s58
	s_waitcnt lgkmcnt(0)
	v_fma_f32 v3, v102, v0, v68
	v_fmac_f32_e32 v69, v103, v0
	ds_write2st64_b32 v2, v3, v69 offset0:34 offset1:35
	ds_read2st64_b32 v[68:69], v2 offset0:36 offset1:37
	s_waitcnt lgkmcnt(0)
	v_fma_f32 v3, v104, v0, v68
	v_fmac_f32_e32 v69, v105, v0
	ds_write2st64_b32 v2, v3, v69 offset0:36 offset1:37
	ds_read2st64_b32 v[68:69], v2 offset0:38 offset1:39
	s_waitcnt lgkmcnt(0)
	v_fma_f32 v3, v106, v0, v68
	v_fmac_f32_e32 v69, v107, v0
	ds_write2st64_b32 v2, v3, v69 offset0:38 offset1:39
	ds_read2st64_b32 v[68:69], v2 offset0:40 offset1:41
	s_waitcnt lgkmcnt(0)
	v_fma_f32 v3, v108, v0, v68
	v_fmac_f32_e32 v69, v109, v0
	ds_write2st64_b32 v2, v3, v69 offset0:40 offset1:41
	ds_read2st64_b32 v[68:69], v2 offset0:42 offset1:43
	s_waitcnt lgkmcnt(0)
	v_fma_f32 v3, v110, v0, v68
	v_fmac_f32_e32 v69, v111, v0
	ds_write2st64_b32 v2, v3, v69 offset0:42 offset1:43
	ds_read2st64_b32 v[68:69], v2 offset0:44 offset1:45
	s_waitcnt lgkmcnt(0)
	v_fma_f32 v3, v112, v0, v68
	v_fmac_f32_e32 v69, v113, v0
	ds_write2st64_b32 v2, v3, v69 offset0:44 offset1:45
	ds_read2st64_b32 v[68:69], v2 offset0:46 offset1:47
	s_waitcnt lgkmcnt(0)
	v_fma_f32 v3, v114, v0, v68
	v_fmac_f32_e32 v69, v115, v0
	ds_write2st64_b32 v2, v3, v69 offset0:46 offset1:47
	s_nop 0
	v_lshlrev_b32_e32 v175, 4, v189
	v_mov_b32_e32 v0, v175
	global_load_dwordx4 v[80:83], v0, s[0:1]
	global_load_dwordx4 v[68:71], v0, s[0:1] offset:1024
	global_load_dwordx4 v[72:75], v0, s[0:1] offset:2048
	global_load_dwordx4 v[76:79], v0, s[0:1] offset:3072
	v_lshl_add_u64 v[84:85], s[0:1], 0, v[0:1]
	v_add_co_u32_e32 v96, vcc, 0x1000, v84
	v_ashrrev_i32_e32 v2, 4, v189
	s_nop 0
	v_addc_co_u32_e32 v97, vcc, 0, v85, vcc
	global_load_dwordx4 v[84:87], v[96:97], off
	global_load_dwordx4 v[88:91], v[96:97], off offset:1024
	global_load_dwordx4 v[92:95], v[96:97], off offset:2048
	s_nop 0
	global_load_dwordx4 v[96:99], v[96:97], off offset:3072
	v_add_u32_e32 v172, s76, v175
	v_bfe_u32 v173, v189, 2, 2
	v_mov_b32_e32 v0, v175
	s_mov_b64 s[0:1], -1
	v_lshlrev_b32_e32 v176, 2, v2
	s_cbranch_scc0 .LBB0_746
	v_readlane_b32 s6, v253, 61
	s_max_i32 s2, s6, 0x1ff
	s_addk_i32 s2, 0xfe01
	s_lshl_b64 s[4:5], s[2:3], 7
	s_lshl_b64 s[0:1], s[80:81], 12
	s_and_b32 s3, s5, 0x7f
	s_and_b32 s4, s4, 0xffffe000
	v_readlane_b32 s5, v255, 51
	s_add_u32 s62, s5, s4
	v_readlane_b32 s4, v255, 52
	s_addc_u32 s63, s4, s3
	s_lshr_b32 s3, s2, 6
	s_andn2_b32 s2, s2, 63
	s_add_i32 s31, s3, 2
	s_or_b32 s30, s2, 63
	s_lshl_b64 s[0:1], s[0:1], 1
	v_readlane_b32 s3, v255, 46
	s_add_u32 s0, s3, s0
	v_readlane_b32 s3, v255, 47
	s_addc_u32 s1, s3, s1
	v_lshl_add_u64 v[100:101], s[0:1], 0, v[0:1]
	v_add_co_u32_e32 v100, vcc, s36, v100
	v_lshlrev_b32_e32 v174, 2, v2
	s_nop 0
	v_addc_co_u32_e32 v101, vcc, 0, v101, vcc
	global_load_dwordx4 v[128:131], v[100:101], off offset:3072
	global_load_dwordx4 v[124:127], v[100:101], off offset:2048
	global_load_dwordx4 v[120:123], v[100:101], off offset:1024
	global_load_dwordx4 v[116:119], v[100:101], off
	global_load_dwordx4 v[112:115], v0, s[0:1] offset:3072
	global_load_dwordx4 v[108:111], v0, s[0:1] offset:2048
	global_load_dwordx4 v[104:107], v0, s[0:1] offset:1024
	s_nop 0
	global_load_dwordx4 v[100:103], v0, s[0:1]
	v_sub_u32_e32 v0, s6, v174
	v_readlane_b32 s0, v253, 63
	v_subrev_u32_e32 v177, s2, v0
	v_mov_b32_e32 v2, v1
	v_sub_u32_e32 v0, s0, v174
	v_readlane_b32 s0, v254, 4
	v_subrev_u32_e32 v178, s2, v0
	v_mov_b32_e32 v3, v1
	v_sub_u32_e32 v0, s0, v174
	v_readlane_b32 s0, v255, 53
	v_subrev_u32_e32 v179, s2, v0
	s_add_i32 s36, s90, 0xfffffe04
	v_sub_u32_e32 v0, s0, v174
	v_subrev_u32_e32 v180, s2, v0
	v_mov_b32_e32 v0, v1
	v_mov_b64_e32 v[142:143], v[2:3]
	v_mov_b64_e32 v[138:139], v[2:3]
	v_mov_b64_e32 v[134:135], v[2:3]
	v_mov_b64_e32 v[146:147], v[2:3]
	v_mov_b32_e32 v181, 0xf149f2ca
	v_mov_b32_e32 v182, 0
	v_mov_b64_e32 v[140:141], v[0:1]
	v_mov_b64_e32 v[136:137], v[0:1]
	v_mov_b64_e32 v[132:133], v[0:1]
	v_mov_b64_e32 v[144:145], v[0:1]
	.p2align 6
